# P1 cumsum: wave-wide inclusive scan via row-based DPP scan (row_shr 1/2/4/8, row_bcast 15/31) instead of six ds_bpermute round trips
# baseline (speedup 1.0000x reference)
.LBB0_172:
	s_ashr_i32 s41, s40, 31
	s_lshl_b64 s[42:43], s[40:41], 14
	v_lshl_add_u64 v[8:9], v[4:5], 0, s[42:43]
	global_load_dwordx4 v[0:3], v[8:9], off
	global_load_dwordx4 v[20:23], v[8:9], off offset:16
	s_waitcnt vmcnt(1)
	v_add_f32_e32 v1, v0, v1
	v_add_f32_e32 v10, v2, v1
	v_add_f32_e32 v11, v3, v10
	s_waitcnt vmcnt(0)
	v_add_f32_e32 v8, v20, v11
	v_add_f32_e32 v9, v21, v8
	v_add_f32_e32 v2, v22, v9
	v_add_f32_e32 v3, v23, v2
	v_mov_b32_e32 v19, v3
	s_nop 1
	v_add_f32_dpp v19, v19, v19 row_shr:1 row_mask:0xf bank_mask:0xf bound_ctrl:0
	s_nop 1
	v_add_f32_dpp v19, v19, v19 row_shr:2 row_mask:0xf bank_mask:0xf bound_ctrl:0
	s_nop 1
	v_add_f32_dpp v19, v19, v19 row_shr:4 row_mask:0xf bank_mask:0xf bound_ctrl:0
	s_nop 1
	v_add_f32_dpp v19, v19, v19 row_shr:8 row_mask:0xf bank_mask:0xf bound_ctrl:0
	s_nop 1
	v_add_f32_dpp v19, v19, v19 row_bcast:15 row_mask:0xa bank_mask:0xf
	s_nop 1
	v_add_f32_dpp v19, v19, v19 row_bcast:31 row_mask:0xc bank_mask:0xf
	v_mov_b32_e32 v12, v19
	s_and_saveexec_b64 s[42:43], s[6:7]
	v_mov_b32_e32 v20, s39
	ds_write_b32 v20, v19
	s_or_b64 exec, exec, s[42:43]
	v_cndmask_b32_e64 v12, v19, v12, s[18:19]
	s_and_b64 vcc, exec, s[20:21]
	v_sub_f32_e32 v12, v12, v3
	s_waitcnt lgkmcnt(0)
	s_barrier
	s_cbranch_vccnz .LBB0_171
	s_and_b64 vcc, exec, s[22:23]
	s_mov_b32 s42, 0
	s_cbranch_vccnz .LBB0_179
	s_mov_b32 s43, s46
